# deferred weight conversion moved to the start of the cross-attn step on workgroups 128..255 (before their GEMM tile), with a workgroup barrier after it
# speedup vs baseline: 1.0222x; 1.0079x over previous
; #define LAS __attribute__((address_space(3)))
; __device__ __forceinline__ void weights_deferred(const Params& P, LAS unsigned char* lds, int l, int part, int nparts) {
;     int tid = threadIdx.x; asm volatile("" : "+v"(tid));
;     const int lane = tid & 63, wave = __builtin_amdgcn_readfirstlane(tid >> 6);
;     LAS float* scr = (LAS float*)(lds + wave * 16384);
;     for (int r = part * NW + wave; r < W_NOKV; r += nparts * NW) weight_item(P, P.ws, scr, l, r, lane);
; }
; __global__ void __launch_bounds__(512, 2) mega_fwd(Params P) {
;     ...
;         if (s == 2 || s == 5 || step == 0) {
;             pg8::Gemm g; pg8::StaticOrder S; pg8::EpiScale E; const float* ssp = SS;
;             if (step == 0) { ssp = (const float*)(ws + WS_SSM); g = pg8::Gemm{(const bf16_t*)(ws + WS_MEMB), (const bf16_t*)(ws + WS_WKV), 512, 8192, D}; S.init(512, 8192, G, (bxs + 64) % G);
;                 E = pg8::EpiScale{(bf16_t*)(ws + WS_MEMKV), 1024, 1.0f, 1, P.out + OFF_MK}; }
;             else if (s == 2) { g = pg8::Gemm{XB, (const bf16_t*)(ws + WS_WIN) + (size_t)l * DIN * D, T, DIN, D}; S.init(T, DIN, G, bxs);
;                 E = pg8::EpiScale{Z, DIN, 1.0f, 0, nullptr}; }
;             else { g = pg8::Gemm{XB, (const bf16_t*)(ws + WS_WXQ) + (size_t)l * D * D, TP, D, D}; S.init(TP, D, G, bxs);
;                 E = pg8::EpiScale{Q2, D, 0.0625f * LOG2E, 0, nullptr}; }
;             pg8::gemm_phase(lds, g, S, E, ssp);
.LBB0_278:
	v_readlane_b32 s0, v253, 0
	v_readlane_b32 s1, v254, 56
	s_cmp_lt_u32 s0, 0x80
	s_cbranch_scc1 .Lwd_skip
	s_cmp_lg_u32 s96, 0x100
	s_cbranch_scc1 .Lwd_skip
	s_mov_b32 s2, 0
	s_cmp_eq_u32 s1, 5
	s_cselect_b32 s2, 1, s2
	s_cmp_eq_u32 s1, 14
	s_cselect_b32 s2, 2, s2
	s_cmp_eq_u32 s1, 23
	s_cselect_b32 s2, 3, s2
	s_cmp_eq_u32 s2, 0
	s_cbranch_scc0 .Lwd_entry

; #define LAS __attribute__((address_space(3)))
; __device__ __forceinline__ void weights_deferred(const Params& P, LAS unsigned char* lds, int l, int part, int nparts) {
;     int tid = threadIdx.x; asm volatile("" : "+v"(tid));
;     const int lane = tid & 63, wave = __builtin_amdgcn_readfirstlane(tid >> 6);
;     LAS float* scr = (LAS float*)(lds + wave * 16384);
;     for (int r = part * NW + wave; r < W_NOKV; r += nparts * NW) weight_item(P, P.ws, scr, l, r, lane);
; }
; __device__ __forceinline__ void prologue(const Params& P, LAS unsigned char* lds, int G, int vcu) {
;     int tid = threadIdx.x; asm volatile("" : "+v"(tid));
;     const int lane = tid & 63, wave = __builtin_amdgcn_readfirstlane(tid >> 6);
;     LAS float* scr = (LAS float*)(lds + wave * 16384);
;     unsigned char* ws = P.ws;
;     const int gw = vcu * NW + wave, NGW = G * NW;
;     for (int it = gw; it < NL * W_PER_L; it += NGW) weight_item(P, ws, scr, it / W_PER_L, it % W_PER_L, lane);
.Lwd_entry:
	v_writelane_b32 v250, s0, 0
	v_writelane_b32 v250, s1, 1
	v_writelane_b32 v250, s2, 2
	v_writelane_b32 v250, s3, 3
	v_writelane_b32 v250, s4, 4
	v_writelane_b32 v250, s5, 5
	v_writelane_b32 v250, s6, 6
	v_writelane_b32 v250, s7, 7
	v_writelane_b32 v250, s8, 8
	v_writelane_b32 v250, s9, 9
	v_writelane_b32 v250, s10, 10
	v_writelane_b32 v250, s11, 11
	v_writelane_b32 v250, s12, 12
	v_writelane_b32 v250, s13, 13
	v_writelane_b32 v250, s14, 14
	v_writelane_b32 v250, s15, 15
	v_writelane_b32 v250, s16, 16
	v_writelane_b32 v250, s17, 17
	v_writelane_b32 v250, s18, 18
	v_writelane_b32 v250, s19, 19
	v_writelane_b32 v250, s20, 20
	v_writelane_b32 v250, s21, 21
	v_writelane_b32 v250, s22, 22
	v_writelane_b32 v250, s23, 23
	v_writelane_b32 v250, s24, 24
	v_writelane_b32 v250, s25, 25
	v_writelane_b32 v250, s26, 26
	v_writelane_b32 v250, s27, 27
	v_writelane_b32 v250, s28, 28
	v_writelane_b32 v250, s29, 29
	v_writelane_b32 v250, s30, 30
	v_writelane_b32 v250, s31, 31
	v_writelane_b32 v250, s32, 32
	v_writelane_b32 v250, s33, 33
	v_writelane_b32 v250, s34, 34
	v_writelane_b32 v250, s35, 35
	v_writelane_b32 v250, s36, 36
	v_writelane_b32 v250, s37, 37
	v_writelane_b32 v250, s38, 38
	v_writelane_b32 v250, s39, 39
	v_writelane_b32 v250, s40, 40
	v_writelane_b32 v250, s41, 41
	v_writelane_b32 v250, s42, 42
	v_writelane_b32 v250, s43, 43
	v_writelane_b32 v250, s44, 44
	v_writelane_b32 v250, s45, 45
	v_writelane_b32 v250, s46, 46
	v_writelane_b32 v250, s47, 47
	v_writelane_b32 v250, s48, 48
	v_writelane_b32 v250, s49, 49
	v_writelane_b32 v250, s50, 50
	v_writelane_b32 v250, s51, 51
	v_writelane_b32 v250, s52, 52
	v_writelane_b32 v250, s53, 53
	v_writelane_b32 v250, s54, 54
	v_writelane_b32 v250, s55, 55
	v_writelane_b32 v250, s56, 56
	v_writelane_b32 v250, s57, 57
	v_writelane_b32 v250, s58, 58
	v_writelane_b32 v250, s59, 59
	v_writelane_b32 v250, s60, 60
	v_writelane_b32 v250, s61, 61
	v_writelane_b32 v250, s62, 62
	v_writelane_b32 v250, s63, 63
	v_writelane_b32 v251, s64, 0
	v_writelane_b32 v251, s65, 1
	v_writelane_b32 v251, s66, 2
	v_writelane_b32 v251, s67, 3
	v_writelane_b32 v251, s68, 4
	v_writelane_b32 v251, s69, 5
	v_writelane_b32 v251, s70, 6
	v_writelane_b32 v251, s71, 7
	v_writelane_b32 v251, s72, 8
	v_writelane_b32 v251, s73, 9
	v_writelane_b32 v251, s74, 10
	v_writelane_b32 v251, s75, 11
	v_writelane_b32 v251, s76, 12
	v_writelane_b32 v251, s77, 13
	v_writelane_b32 v251, s78, 14
	v_writelane_b32 v251, s79, 15
	s_add_i32 s3, s0, 0xffffff80
	s_mul_i32 s2, s2, 0x3000
	s_lshl_b32 s3, s3, 3
	s_add_i32 s61, s2, 0x2bff
	s_add_i32 s26, s2, s3
	v_readlane_b32 s0, v255, 60
	v_readlane_b32 s1, v255, 61
	v_mov_b32_e32 v1, v208
	s_mov_b32 s32, 1
	s_movk_i32 s60, 0x400
	v_readfirstlane_b32 s2, v1
	v_and_b32_e32 v34, 63, v1
	s_ashr_i32 s27, s2, 6
	s_add_i32 s26, s26, s27
	s_lshl_b32 s2, s27, 14
	s_add_i32 s6, s2, 0
	s_add_u32 s28, s94, 0x18000000
	s_addc_u32 s29, s95, 0
	s_add_u32 s30, s94, 0x1d800000
	s_addc_u32 s31, s95, 0
	s_add_u32 s34, s94, 0x22800000
	s_addc_u32 s35, s95, 0
	s_add_u32 s36, s94, 0x22000000
	s_addc_u32 s37, s95, 0
	s_load_dwordx16 s[8:23], s[0:1], 0x80
	s_add_u32 s38, s94, 0x21800000
	s_addc_u32 s39, s95, 0
	v_and_b32_e32 v3, 7, v1
	s_add_u32 s40, s94, 0x20400000
	s_load_dwordx16 s[44:59], s[0:1], 0x40
	v_mov_b32_e32 v37, 0
	v_lshlrev_b32_e32 v36, 4, v3
	s_addc_u32 s41, s95, 0
	s_load_dwordx16 s[64:79], s[0:1], 0xc0
	v_lshrrev_b32_e32 v1, 3, v34
	v_lshl_add_u64 v[4:5], s[94:95], 0, v[36:37]
	s_mov_b64 s[2:3], 0x23000000
	s_waitcnt lgkmcnt(0)
	s_cmp_lg_u64 s[20:21], 0
	v_lshlrev_b32_e32 v2, 2, v3
	v_lshlrev_b32_e32 v38, 3, v3
	v_mul_u32_u24_e32 v3, 0x420, v3
	v_lshl_add_u64 v[40:41], v[4:5], 0, s[2:3]
	v_lshlrev_b32_e32 v4, 2, v1
	s_cselect_b64 s[2:3], -1, 0
	s_cmp_lg_u64 s[18:19], 0
	v_add_u32_e32 v35, s6, v36
	v_add3_u32 v53, s6, v3, v4
	s_cselect_b64 s[6:7], -1, 0
	s_cmp_lg_u64 s[14:15], 0
	s_cselect_b64 s[8:9], -1, 0
	s_cmp_lg_u64 s[54:55], 0
	s_cselect_b64 s[10:11], -1, 0
	s_cmp_lg_u64 s[70:71], 0
	s_cselect_b64 s[12:13], -1, 0
	s_cmp_lg_u64 s[46:47], 0
	v_mul_u32_u24_e32 v39, 0x84, v1
	v_or_b32_e32 v45, 8, v1
	v_or_b32_e32 v47, 16, v1
	v_or_b32_e32 v51, 24, v1
	v_cndmask_b32_e64 v55, 0, 1, s[2:3]
	v_lshlrev_b32_e32 v42, 2, v2
	v_mov_b32_e32 v57, 0x8000
	v_mov_b32_e32 v59, 0x10000
	v_mov_b32_e32 v60, 0x18000
	v_mov_b32_e32 v61, 0x20000
	v_mov_b32_e32 v62, 0x28000
	v_mov_b32_e32 v63, 0x30000
	v_mov_b32_e32 v64, 0x38000
	s_cselect_b64 s[14:15], -1, 0
	s_lshl_b32 s42, s26, 1
	s_lshl_b32 s43, s60, 1
	s_lshl_b32 s44, s26, 5
	s_lshl_b32 s45, s60, 5
	s_movk_i32 s46, 0x2800
	s_movk_i32 s47, 0x2c00
	s_mov_b32 s48, s26
	s_mov_b32 s17, 0
	s_branch .LBB0_11
; #define LAS __attribute__((address_space(3)))
; __device__ __forceinline__ void weights_deferred(const Params& P, LAS unsigned char* lds, int l, int part, int nparts) {
;     int tid = threadIdx.x; asm volatile("" : "+v"(tid));
;     const int lane = tid & 63, wave = __builtin_amdgcn_readfirstlane(tid >> 6);
;     LAS float* scr = (LAS float*)(lds + wave * 16384);
;     for (int r = part * NW + wave; r < W_NOKV; r += nparts * NW) weight_item(P, P.ws, scr, l, r, lane);
; }
.Lwd_return:
	s_waitcnt lgkmcnt(0)
	s_barrier
	v_mov_b32_e32 v1, 0
	v_readlane_b32 s0, v250, 0
	v_readlane_b32 s1, v250, 1
	v_readlane_b32 s2, v250, 2
	v_readlane_b32 s3, v250, 3
	v_readlane_b32 s4, v250, 4
	v_readlane_b32 s5, v250, 5
	v_readlane_b32 s6, v250, 6
	v_readlane_b32 s7, v250, 7
	v_readlane_b32 s8, v250, 8
	v_readlane_b32 s9, v250, 9
	v_readlane_b32 s10, v250, 10
	v_readlane_b32 s11, v250, 11
	v_readlane_b32 s12, v250, 12
	v_readlane_b32 s13, v250, 13
	v_readlane_b32 s14, v250, 14
	v_readlane_b32 s15, v250, 15
	v_readlane_b32 s16, v250, 16
	v_readlane_b32 s17, v250, 17
	v_readlane_b32 s18, v250, 18
	v_readlane_b32 s19, v250, 19
	v_readlane_b32 s20, v250, 20
	v_readlane_b32 s21, v250, 21
	v_readlane_b32 s22, v250, 22
	v_readlane_b32 s23, v250, 23
	v_readlane_b32 s24, v250, 24
	v_readlane_b32 s25, v250, 25
	v_readlane_b32 s26, v250, 26
	v_readlane_b32 s27, v250, 27
	v_readlane_b32 s28, v250, 28
	v_readlane_b32 s29, v250, 29
	v_readlane_b32 s30, v250, 30
	v_readlane_b32 s31, v250, 31
	v_readlane_b32 s32, v250, 32
	v_readlane_b32 s33, v250, 33
	v_readlane_b32 s34, v250, 34
	v_readlane_b32 s35, v250, 35
	v_readlane_b32 s36, v250, 36
	v_readlane_b32 s37, v250, 37
	v_readlane_b32 s38, v250, 38
	v_readlane_b32 s39, v250, 39
	v_readlane_b32 s40, v250, 40
	v_readlane_b32 s41, v250, 41
	v_readlane_b32 s42, v250, 42
	v_readlane_b32 s43, v250, 43
	v_readlane_b32 s44, v250, 44
	v_readlane_b32 s45, v250, 45
	v_readlane_b32 s46, v250, 46
	v_readlane_b32 s47, v250, 47
	v_readlane_b32 s48, v250, 48
	v_readlane_b32 s49, v250, 49
	v_readlane_b32 s50, v250, 50
	v_readlane_b32 s51, v250, 51
	v_readlane_b32 s52, v250, 52
	v_readlane_b32 s53, v250, 53
	v_readlane_b32 s54, v250, 54
	v_readlane_b32 s55, v250, 55
	v_readlane_b32 s56, v250, 56
	v_readlane_b32 s57, v250, 57
	v_readlane_b32 s58, v250, 58
	v_readlane_b32 s59, v250, 59
	v_readlane_b32 s60, v250, 60
	v_readlane_b32 s61, v250, 61
	v_readlane_b32 s62, v250, 62
	v_readlane_b32 s63, v250, 63
	v_readlane_b32 s64, v251, 0
	v_readlane_b32 s65, v251, 1
	v_readlane_b32 s66, v251, 2
	v_readlane_b32 s67, v251, 3
	v_readlane_b32 s68, v251, 4
	v_readlane_b32 s69, v251, 5
	v_readlane_b32 s70, v251, 6
	v_readlane_b32 s71, v251, 7
	v_readlane_b32 s72, v251, 8
	v_readlane_b32 s73, v251, 9
	v_readlane_b32 s74, v251, 10
	v_readlane_b32 s75, v251, 11
	v_readlane_b32 s76, v251, 12
	v_readlane_b32 s77, v251, 13
	v_readlane_b32 s78, v251, 14
	v_readlane_b32 s79, v251, 15
	s_branch .Lwd_skip
